# grid barrier: acquire-side buffer_inv issued before polling the generation flag instead of after
# speedup vs baseline: 1.0153x; 1.0130x over previous
.LBB0_1515:
	s_or_b64 exec, exec, s[4:5]
	v_cvt_f32_u32_e32 v4, v2
	s_waitcnt vmcnt(0)
	v_readfirstlane_b32 s4, v3
	v_sub_u32_e32 v3, 0, v2
	v_rcp_iflag_f32_e32 v4, v4
	v_add_u32_e32 v5, s4, v1
	v_mul_f32_e32 v4, 0x4f7ffffe, v4
	v_cvt_u32_f32_e32 v4, v4
	v_mul_lo_u32 v1, v3, v4
	v_mul_hi_u32 v1, v4, v1
	v_add_u32_e32 v1, v4, v1
	v_mul_hi_u32 v1, v5, v1
	v_mul_lo_u32 v3, v1, v2
	v_sub_u32_e32 v3, v5, v3
	v_add_u32_e32 v4, 1, v1
	v_cmp_ge_u32_e32 vcc, v3, v2
	s_nop 1
	v_cndmask_b32_e32 v1, v1, v4, vcc
	v_sub_u32_e32 v4, v3, v2
	v_cndmask_b32_e32 v3, v3, v4, vcc
	v_add_u32_e32 v4, 1, v1
	v_cmp_ge_u32_e32 vcc, v3, v2
	v_add_u32_e32 v3, 1, v5
	s_nop 0
	v_cndmask_b32_e32 v1, v1, v4, vcc
	v_mul_lo_u32 v4, v2, v1
	v_add_u32_e32 v2, v4, v2
	v_cmp_ne_u32_e32 vcc, v3, v2
	s_and_saveexec_b64 s[4:5], vcc
	s_xor_b64 s[4:5], exec, s[4:5]
	s_cbranch_execz .LBB0_1529
	buffer_inv sc1
	v_readlane_b32 s24, v254, 51
	v_readlane_b32 s25, v254, 52
	s_waitcnt lgkmcnt(0)
	s_nop 3
	global_load_dword v0, v145, s[24:25] sc1
	s_waitcnt vmcnt(0)
	v_cmp_eq_u32_e32 vcc, v0, v1
	s_and_saveexec_b64 s[24:25], vcc
	s_cbranch_execz .LBB0_1528
	s_mov_b32 s33, 1
	s_mov_b64 s[28:29], 0
	s_branch .LBB0_1519

.LBB0_1528:
	s_or_b64 exec, exec, s[24:25]
	s_waitcnt vmcnt(0)
	s_waitcnt vmcnt(0)

.LBB0_1532:
	s_or_b64 exec, exec, s[24:25]
	s_waitcnt vmcnt(0)
	buffer_inv sc1
	v_readfirstlane_b32 s4, v2
	v_cvt_f32_u32_e32 v2, v0
	v_sub_u32_e32 v3, 0, v0
	v_add_u32_e32 v1, s4, v1
	v_readlane_b32 s4, v254, 55
	v_rcp_iflag_f32_e32 v2, v2
	v_readlane_b32 s5, v254, 56
	s_mov_b64 s[24:25], -1
	v_mul_f32_e32 v2, 0x4f7ffffe, v2
	v_cvt_u32_f32_e32 v2, v2
	v_mul_lo_u32 v3, v3, v2
	v_mul_hi_u32 v3, v2, v3
	v_add_u32_e32 v2, v2, v3
	v_mul_hi_u32 v2, v1, v2
	v_mul_lo_u32 v3, v2, v0
	v_sub_u32_e32 v3, v1, v3
	v_cmp_ge_u32_e32 vcc, v3, v0
	v_add_u32_e32 v4, 1, v2
	v_add_u32_e32 v1, 1, v1
	v_cndmask_b32_e32 v2, v2, v4, vcc
	v_sub_u32_e32 v4, v3, v0
	v_cndmask_b32_e32 v3, v3, v4, vcc
	v_cmp_ge_u32_e32 vcc, v3, v0
	v_add_u32_e32 v3, 1, v2
	s_nop 0
	v_cndmask_b32_e32 v2, v2, v3, vcc
	v_mul_lo_u32 v3, v0, v2
	v_add_u32_e32 v0, v3, v0
	v_cmp_ne_u32_e32 vcc, v1, v0
	v_mov_b64_e32 v[0:1], s[4:5]
	s_and_saveexec_b64 s[4:5], vcc
	s_cbranch_execz .LBB0_1544
	v_readlane_b32 s24, v254, 55
	v_readlane_b32 s25, v254, 56
	s_mov_b64 s[28:29], 0
	s_nop 3
	global_load_dword v0, v145, s[24:25] sc1
	s_waitcnt vmcnt(0)
	v_cmp_eq_u32_e32 vcc, v0, v2
	s_and_saveexec_b64 s[24:25], vcc
	s_cbranch_execz .LBB0_1543
	s_mov_b32 s33, 1
	s_branch .LBB0_1536

.LBB0_1546:
	s_or_b64 exec, exec, s[4:5]
	s_mov_b64 s[4:5], exec
	v_mbcnt_lo_u32_b32 v0, s4, 0
	v_mbcnt_hi_u32_b32 v0, s5, v0
	v_cmp_eq_u32_e32 vcc, 0, v0
	s_waitcnt vmcnt(0)
	s_and_saveexec_b64 s[24:25], vcc
	s_cbranch_execnz .LBB0_1547
	s_getpc_b64 s[98:99]
